# attention PV section software-pipelined: LDS transpose reads issued 4 rounds ahead with counted lgkmcnt
# speedup vs baseline: 1.0103x; 1.0103x over previous
; #define LAS __attribute__((address_space(3)))
; __device__ __forceinline__ unsigned pk2(float lo, float hi) { f32x2_t v = {lo, hi}; bf16x2_t b = __builtin_convertvector(v, bf16x2_t); return __builtin_bit_cast(unsigned, b); }
; __device__ __forceinline__ void attn_unit(const Args& c, int l, int b, int h, int qb, float lam, float lam_init, LAS unsigned char* lds) {
;     ...
;             const float mnew = fmaxf(mrow[m], mx);
;             const float alpha = __builtin_amdgcn_exp2f(mrow[m] - mnew);
;             mrow[m] = mnew;
;             float ps = 0.f;
; #pragma unroll
;             for (int kb = 0; kb < 8; ++kb)
; #pragma unroll
;                 for (int e = 0; e < 4; ++e) { s[kb][e] = __builtin_amdgcn_exp2f(s[kb][e] - mnew); ps += s[kb][e]; }
;             lrow[m] = lrow[m] * alpha + ps;
;             if (__builtin_amdgcn_ballot_w64(alpha != 1.0f) != 0ull) {
; #pragma unroll
;                 for (int vb = 0; vb < 8; ++vb) O[m][vb] = O[m][vb] * alpha;
;             }
; #pragma unroll
;             for (int s2 = 0; s2 < 4; ++s2) { u32x4v o; o.x = pk2(s[2 * s2][0], s[2 * s2][1]); o.y = pk2(s[2 * s2][2], s[2 * s2][3]); o.z = pk2(s[2 * s2 + 1][0], s[2 * s2 + 1][1]); o.w = pk2(s[2 * s2 + 1][2], s[2 * s2 + 1][3]);
;                 pf[m][s2] = __builtin_bit_cast(bf16x8, o); }
;         }
; #pragma unroll
;         for (int vb = 0; vb < 8; ++vb)
; #pragma unroll
;             for (int s2 = 0; s2 < 4; ++s2) {
;                 const v4i16_t lo = __builtin_amdgcn_ds_read_tr16_b64_v4i16((LAS v4i16_t*)(Vs + (32 * s2 + 4 * q4 + r4) * 136 + 16 * vb + 4 * c4));
;                 const v4i16_t hi = __builtin_amdgcn_ds_read_tr16_b64_v4i16((LAS v4i16_t*)(Vs + (32 * s2 + 16 + 4 * q4 + r4) * 136 + 16 * vb + 4 * c4));
;                 const bf16x8 vfr = (bf16x8){lo[0], lo[1], lo[2], lo[3], hi[0], hi[1], hi[2], hi[3]};
.LBB0_255:
	v_sub_f32_e32 v174, v174, v214
	v_exp_f32_e32 v174, v174
	v_sub_f32_e32 v175, v175, v214
	v_exp_f32_e32 v175, v175
	v_sub_f32_e32 v176, v176, v214
	v_exp_f32_e32 v176, v176
	v_sub_f32_e32 v177, v177, v214
	v_exp_f32_e32 v177, v177
	v_sub_f32_e32 v170, v170, v214
	v_add_f32_e32 v180, 0, v174
	v_exp_f32_e32 v170, v170
	v_sub_f32_e32 v171, v171, v214
	v_add_f32_e32 v180, v175, v180
	v_exp_f32_e32 v171, v171
	v_sub_f32_e32 v172, v172, v214
	v_add_f32_e32 v180, v176, v180
	v_exp_f32_e32 v172, v172
	v_sub_f32_e32 v173, v173, v214
	v_add_f32_e32 v180, v177, v180
	v_exp_f32_e32 v173, v173
	v_sub_f32_e32 v166, v166, v214
	v_add_f32_e32 v180, v170, v180
	v_exp_f32_e32 v166, v166
	v_sub_f32_e32 v167, v167, v214
	v_add_f32_e32 v180, v171, v180
	v_exp_f32_e32 v167, v167
	v_sub_f32_e32 v168, v168, v214
	v_add_f32_e32 v180, v172, v180
	v_exp_f32_e32 v168, v168
	v_sub_f32_e32 v169, v169, v214
	v_add_f32_e32 v180, v173, v180
	v_exp_f32_e32 v169, v169
	v_sub_f32_e32 v162, v162, v214
	v_add_f32_e32 v180, v166, v180
	v_exp_f32_e32 v162, v162
	v_sub_f32_e32 v163, v163, v214
	v_add_f32_e32 v180, v167, v180
	v_exp_f32_e32 v163, v163
	v_sub_f32_e32 v164, v164, v214
	v_add_f32_e32 v180, v168, v180
	v_exp_f32_e32 v164, v164
	v_sub_f32_e32 v165, v165, v214
	v_add_f32_e32 v180, v169, v180
	v_exp_f32_e32 v165, v165
	v_sub_f32_e32 v158, v158, v214
	v_add_f32_e32 v180, v162, v180
	v_exp_f32_e32 v158, v158
	v_sub_f32_e32 v159, v159, v214
	v_add_f32_e32 v180, v163, v180
	v_exp_f32_e32 v159, v159
	v_sub_f32_e32 v160, v160, v214
	v_add_f32_e32 v180, v164, v180
	v_exp_f32_e32 v160, v160
	v_sub_f32_e32 v161, v161, v214
	v_add_f32_e32 v180, v165, v180
	v_exp_f32_e32 v161, v161
	v_sub_f32_e32 v154, v154, v214
	v_add_f32_e32 v180, v158, v180
	v_exp_f32_e32 v154, v154
	v_sub_f32_e32 v155, v155, v214
	v_add_f32_e32 v180, v159, v180
	v_exp_f32_e32 v155, v155
	v_sub_f32_e32 v156, v156, v214
	v_add_f32_e32 v180, v160, v180
	v_exp_f32_e32 v156, v156
	v_sub_f32_e32 v157, v157, v214
	v_add_f32_e32 v180, v161, v180
	v_exp_f32_e32 v157, v157
	v_sub_f32_e32 v150, v150, v214
	v_add_f32_e32 v180, v154, v180
	v_exp_f32_e32 v150, v150
	v_sub_f32_e32 v151, v151, v214
	v_add_f32_e32 v180, v155, v180
	v_exp_f32_e32 v151, v151
	v_sub_f32_e32 v152, v152, v214
	v_add_f32_e32 v180, v156, v180
	v_exp_f32_e32 v152, v152
	v_sub_f32_e32 v153, v153, v214
	v_add_f32_e32 v180, v157, v180
	v_exp_f32_e32 v153, v153
	v_sub_f32_e32 v146, v146, v214
	v_add_f32_e32 v180, v150, v180
	v_exp_f32_e32 v181, v146
	v_add_f32_e32 v180, v151, v180
	v_add_f32_e32 v180, v152, v180
	v_add_f32_e32 v180, v153, v180
	v_sub_f32_e32 v147, v147, v214
	v_add_f32_e32 v146, v181, v180
	v_exp_f32_e32 v180, v147
	v_sub_f32_e32 v147, v148, v214
	v_exp_f32_e32 v148, v147
	v_sub_f32_e32 v147, v149, v214
	v_exp_f32_e32 v149, v147
	v_sub_f32_e32 v114, v114, v213
	v_add_f32_e32 v146, v180, v146
	v_exp_f32_e32 v147, v114
	v_sub_f32_e32 v114, v115, v213
	v_add_f32_e32 v146, v148, v146
	v_exp_f32_e32 v182, v114
	v_sub_f32_e32 v114, v116, v213
	v_add_f32_e32 v146, v149, v146
	v_exp_f32_e32 v183, v114
	v_sub_f32_e32 v114, v117, v213
	v_fmac_f32_e32 v146, v216, v192
	v_exp_f32_e32 v192, v114
	v_sub_f32_e32 v114, v118, v213
	v_exp_f32_e32 v118, v114
	v_sub_f32_e32 v114, v119, v213
	v_exp_f32_e32 v119, v114
	v_sub_f32_e32 v114, v120, v213
	v_exp_f32_e32 v120, v114
	v_sub_f32_e32 v114, v121, v213
	v_exp_f32_e32 v121, v114
	v_sub_f32_e32 v114, v122, v213
	v_exp_f32_e32 v216, v114
	v_sub_f32_e32 v114, v123, v213
	v_exp_f32_e32 v217, v114
	v_sub_f32_e32 v114, v124, v213
	v_exp_f32_e32 v218, v114
	v_sub_f32_e32 v114, v125, v213
	v_exp_f32_e32 v219, v114
	v_sub_f32_e32 v114, v126, v213
	v_exp_f32_e32 v220, v114
	v_sub_f32_e32 v114, v127, v213
	v_exp_f32_e32 v221, v114
	v_sub_f32_e32 v114, v128, v213
	v_exp_f32_e32 v222, v114
	v_sub_f32_e32 v114, v129, v213
	v_exp_f32_e32 v223, v114
	v_sub_f32_e32 v114, v130, v213
	v_cvt_pk_bf16_f32 v130, v147, v182
	v_add_f32_e32 v147, 0, v147
	v_add_f32_e32 v147, v182, v147
	v_add_f32_e32 v147, v183, v147
	v_exp_f32_e32 v224, v114
	v_sub_f32_e32 v114, v131, v213
	v_add_f32_e32 v147, v192, v147
	v_exp_f32_e32 v225, v114
	v_sub_f32_e32 v114, v132, v213
	v_cvt_pk_bf16_f32 v132, v118, v119
	v_add_f32_e32 v118, v118, v147
	v_add_f32_e32 v118, v119, v118
	v_add_f32_e32 v118, v120, v118
	v_add_f32_e32 v118, v121, v118
	v_add_f32_e32 v118, v216, v118
	v_add_f32_e32 v118, v217, v118
	v_add_f32_e32 v118, v218, v118
	v_add_f32_e32 v118, v219, v118
	v_add_f32_e32 v118, v220, v118
	v_add_f32_e32 v118, v221, v118
	v_exp_f32_e32 v226, v114
	v_sub_f32_e32 v114, v133, v213
	v_add_f32_e32 v118, v222, v118
	v_exp_f32_e32 v227, v114
	v_sub_f32_e32 v114, v134, v213
	v_add_f32_e32 v118, v223, v118
	v_exp_f32_e32 v134, v114
	v_sub_f32_e32 v114, v135, v213
	v_add_f32_e32 v118, v224, v118
	v_exp_f32_e32 v135, v114
	v_sub_f32_e32 v114, v136, v213
	v_add_f32_e32 v118, v225, v118
	v_exp_f32_e32 v136, v114
	v_sub_f32_e32 v114, v137, v213
	v_add_f32_e32 v118, v226, v118
	v_exp_f32_e32 v137, v114
	v_sub_f32_e32 v114, v138, v213
	v_add_f32_e32 v118, v227, v118
	v_exp_f32_e32 v138, v114
	v_sub_f32_e32 v114, v139, v213
	v_add_f32_e32 v118, v134, v118
	v_exp_f32_e32 v139, v114
	v_sub_f32_e32 v114, v140, v213
	v_add_f32_e32 v118, v135, v118
	v_exp_f32_e32 v140, v114
	v_sub_f32_e32 v114, v141, v213
	v_add_f32_e32 v118, v136, v118
	v_exp_f32_e32 v141, v114
	v_sub_f32_e32 v114, v142, v213
	v_add_f32_e32 v118, v137, v118
	v_exp_f32_e32 v142, v114
	v_sub_f32_e32 v114, v143, v213
	v_add_f32_e32 v118, v138, v118
	v_exp_f32_e32 v143, v114
	v_sub_f32_e32 v114, v144, v213
	v_add_f32_e32 v118, v139, v118
	v_exp_f32_e32 v144, v114
	v_sub_f32_e32 v114, v145, v213
	v_add_f32_e32 v118, v140, v118
	v_exp_f32_e32 v145, v114
	v_add_f32_e32 v118, v141, v118
	v_add_f32_e32 v118, v142, v118
	v_add_f32_e32 v118, v143, v118
	v_add_f32_e32 v118, v144, v118
	v_cvt_pk_bf16_f32 v133, v120, v121
	v_add_f32_e32 v147, v145, v118
	v_cvt_pk_bf16_f32 v118, v150, v151
	v_cvt_pk_bf16_f32 v119, v152, v153
	v_cvt_pk_bf16_f32 v121, v148, v149
	ds_read_b64_tr_b16 v[150:151], v210 offset:39168
	ds_read_b64_tr_b16 v[148:149], v210 offset:34816
	ds_read_b64_tr_b16 v[152:153], v210 offset:34848
	v_cvt_pk_bf16_f32 v131, v183, v192
	v_cvt_pk_bf16_f32 v116, v142, v143
	v_cvt_pk_bf16_f32 v117, v144, v145
	v_cvt_pk_bf16_f32 v142, v174, v175
	v_cvt_pk_bf16_f32 v143, v176, v177
	v_cvt_pk_bf16_f32 v144, v170, v171
	v_cvt_pk_bf16_f32 v145, v172, v173
	s_waitcnt lgkmcnt(0)
; #define LAS __attribute__((address_space(3)))
; #define MFMA16(a, b, c) __builtin_amdgcn_mfma_f32_16x16x32_bf16(a, b, c, 0, 0, 0)
; __device__ __forceinline__ void attn_unit(const Args& c, int l, int b, int h, int qb, float lam, float lam_init, LAS unsigned char* lds) {
;     ...
; #pragma unroll
;         for (int vb = 0; vb < 8; ++vb)
; #pragma unroll
;             for (int s2 = 0; s2 < 4; ++s2) {
;                 const v4i16_t lo = __builtin_amdgcn_ds_read_tr16_b64_v4i16((LAS v4i16_t*)(Vs + (32 * s2 + 4 * q4 + r4) * 136 + 16 * vb + 4 * c4));
;                 const v4i16_t hi = __builtin_amdgcn_ds_read_tr16_b64_v4i16((LAS v4i16_t*)(Vs + (32 * s2 + 16 + 4 * q4 + r4) * 136 + 16 * vb + 4 * c4));
;                 const bf16x8 vfr = (bf16x8){lo[0], lo[1], lo[2], lo[3], hi[0], hi[1], hi[2], hi[3]};
;                 O[0][vb] = MFMA16(vfr, pf[0][s2], O[0][vb]); O[1][vb] = MFMA16(vfr, pf[1][s2], O[1][vb]);
;             }
	v_mfma_f32_16x16x32_bf16 v[46:49], v[148:151], v[130:133], v[46:49]
	v_cvt_pk_bf16_f32 v126, v216, v217
	v_cvt_pk_bf16_f32 v127, v218, v219
	v_cvt_pk_bf16_f32 v128, v220, v221
	v_mfma_f32_16x16x32_bf16 v[42:45], v[148:151], v[142:145], v[42:45]
	ds_read_b64_tr_b16 v[148:149], v210 offset:43520
	ds_read_b64_tr_b16 v[150:151], v210 offset:47872
	v_cvt_pk_bf16_f32 v129, v222, v223
	v_cvt_pk_bf16_f32 v114, v138, v139
	v_cvt_pk_bf16_f32 v115, v140, v141
	v_cvt_pk_bf16_f32 v138, v166, v167
	v_cvt_pk_bf16_f32 v139, v168, v169
	v_cvt_pk_bf16_f32 v140, v162, v163
	v_cvt_pk_bf16_f32 v141, v164, v165
	s_waitcnt lgkmcnt(0)
	v_mfma_f32_16x16x32_bf16 v[46:49], v[148:151], v[126:129], v[46:49]
	v_cvt_pk_bf16_f32 v122, v224, v225
	v_cvt_pk_bf16_f32 v123, v226, v227
	v_cvt_pk_bf16_f32 v124, v134, v135
	v_mfma_f32_16x16x32_bf16 v[42:45], v[148:151], v[138:141], v[42:45]
	ds_read_b64_tr_b16 v[148:149], v210 offset:52224
	ds_read_b64_tr_b16 v[150:151], v210 offset:56576
	v_cvt_pk_bf16_f32 v125, v136, v137
	v_cvt_pk_bf16_f32 v134, v158, v159
	v_cvt_pk_bf16_f32 v135, v160, v161
	v_cvt_pk_bf16_f32 v136, v154, v155
	v_cvt_pk_bf16_f32 v137, v156, v157
	s_waitcnt lgkmcnt(0)
	v_mfma_f32_16x16x32_bf16 v[46:49], v[148:151], v[122:125], v[46:49]
	v_cvt_pk_bf16_f32 v120, v181, v180
	s_add_i32 s35, s35, 1
	s_addk_i32 s5, 0x80
	v_mfma_f32_16x16x32_bf16 v[42:45], v[148:151], v[134:137], v[42:45]
	ds_read_b64_tr_b16 v[148:149], v210 offset:60928
	ds_read_b64_tr_b16 v[150:151], v210 offset:65280
	ds_read_b64_tr_b16 v[154:155], v210 offset:39200
	v_fmac_f32_e32 v147, v215, v190
	s_waitcnt lgkmcnt(0)
	v_mfma_f32_16x16x32_bf16 v[46:49], v[148:151], v[114:117], v[46:49]
	s_cmp_lg_u32 s34, s35
	v_mfma_f32_16x16x32_bf16 v[42:45], v[148:151], v[118:121], v[42:45]
	ds_read_b64_tr_b16 v[148:149], v210 offset:43552
	ds_read_b64_tr_b16 v[150:151], v210 offset:47904
	v_mfma_f32_16x16x32_bf16 v[38:41], v[152:155], v[130:133], v[38:41]
	v_mfma_f32_16x16x32_bf16 v[34:37], v[152:155], v[142:145], v[34:37]
	ds_read_b64_tr_b16 v[152:153], v210 offset:52256
	ds_read_b64_tr_b16 v[154:155], v210 offset:56608
	ds_read_b64_tr_b16 v[156:157], v210 offset:60960
	ds_read_b64_tr_b16 v[158:159], v210 offset:65312
	ds_read_b64_tr_b16 v[160:161], v210 offset:34880
	ds_read_b64_tr_b16 v[162:163], v210 offset:39232
	ds_read_b64_tr_b16 v[164:165], v210 offset:43584
	ds_read_b64_tr_b16 v[166:167], v210 offset:47936
	s_waitcnt lgkmcnt(8)
	v_mfma_f32_16x16x32_bf16 v[38:41], v[148:151], v[126:129], v[38:41]
	v_mfma_f32_16x16x32_bf16 v[34:37], v[148:151], v[138:141], v[34:37]
	ds_read_b64_tr_b16 v[148:149], v210 offset:52288
	ds_read_b64_tr_b16 v[150:151], v210 offset:56640
	s_waitcnt lgkmcnt(8)
	v_mfma_f32_16x16x32_bf16 v[38:41], v[152:155], v[122:125], v[38:41]
	v_mfma_f32_16x16x32_bf16 v[34:37], v[152:155], v[134:137], v[34:37]
	ds_read_b64_tr_b16 v[152:153], v210 offset:60992
	ds_read_b64_tr_b16 v[154:155], v210 offset:65344
	s_waitcnt lgkmcnt(8)
	v_mfma_f32_16x16x32_bf16 v[38:41], v[156:159], v[114:117], v[38:41]
	v_mfma_f32_16x16x32_bf16 v[34:37], v[156:159], v[118:121], v[34:37]
	ds_read_b64_tr_b16 v[156:157], v210 offset:34912
	ds_read_b64_tr_b16 v[158:159], v210 offset:39264
	s_waitcnt lgkmcnt(8)
	v_mfma_f32_16x16x32_bf16 v[30:33], v[160:163], v[130:133], v[30:33]
	v_mfma_f32_16x16x32_bf16 v[26:29], v[160:163], v[142:145], v[26:29]
	ds_read_b64_tr_b16 v[160:161], v210 offset:43616
	ds_read_b64_tr_b16 v[162:163], v210 offset:47968
	s_waitcnt lgkmcnt(8)
	v_mfma_f32_16x16x32_bf16 v[30:33], v[164:167], v[126:129], v[30:33]
	v_mfma_f32_16x16x32_bf16 v[26:29], v[164:167], v[138:141], v[26:29]
	ds_read_b64_tr_b16 v[164:165], v210 offset:52320
	ds_read_b64_tr_b16 v[166:167], v210 offset:56672
	s_waitcnt lgkmcnt(8)
	v_mfma_f32_16x16x32_bf16 v[30:33], v[148:151], v[122:125], v[30:33]
	v_mfma_f32_16x16x32_bf16 v[26:29], v[148:151], v[134:137], v[26:29]
	ds_read_b64_tr_b16 v[148:149], v210 offset:61024
	ds_read_b64_tr_b16 v[150:151], v210 offset:65376
	s_waitcnt lgkmcnt(8)
	v_mfma_f32_16x16x32_bf16 v[30:33], v[152:155], v[114:117], v[30:33]
	v_mfma_f32_16x16x32_bf16 v[26:29], v[152:155], v[118:121], v[26:29]
	ds_read_b64_tr_b16 v[152:153], v210 offset:34944
	ds_read_b64_tr_b16 v[154:155], v210 offset:39296
	s_waitcnt lgkmcnt(8)
	v_mfma_f32_16x16x32_bf16 v[62:65], v[156:159], v[130:133], v[62:65]
	v_mfma_f32_16x16x32_bf16 v[58:61], v[156:159], v[142:145], v[58:61]
	ds_read_b64_tr_b16 v[156:157], v210 offset:43648
	ds_read_b64_tr_b16 v[158:159], v210 offset:48000
	s_waitcnt lgkmcnt(8)
; #define LAS __attribute__((address_space(3)))
; #define MFMA16(a, b, c) __builtin_amdgcn_mfma_f32_16x16x32_bf16(a, b, c, 0, 0, 0)
; __device__ __forceinline__ void attn_unit(const Args& c, int l, int b, int h, int qb, float lam, float lam_init, LAS unsigned char* lds) {
;     ...
; #pragma unroll
;         for (int vb = 0; vb < 8; ++vb)
; #pragma unroll
;             for (int s2 = 0; s2 < 4; ++s2) {
;                 const v4i16_t lo = __builtin_amdgcn_ds_read_tr16_b64_v4i16((LAS v4i16_t*)(Vs + (32 * s2 + 4 * q4 + r4) * 136 + 16 * vb + 4 * c4));
;                 const v4i16_t hi = __builtin_amdgcn_ds_read_tr16_b64_v4i16((LAS v4i16_t*)(Vs + (32 * s2 + 16 + 4 * q4 + r4) * 136 + 16 * vb + 4 * c4));
;                 const bf16x8 vfr = (bf16x8){lo[0], lo[1], lo[2], lo[3], hi[0], hi[1], hi[2], hi[3]};
;                 O[0][vb] = MFMA16(vfr, pf[0][s2], O[0][vb]); O[1][vb] = MFMA16(vfr, pf[1][s2], O[1][vb]);
;             }
	v_mfma_f32_16x16x32_bf16 v[62:65], v[160:163], v[126:129], v[62:65]
	v_mfma_f32_16x16x32_bf16 v[58:61], v[160:163], v[138:141], v[58:61]
	ds_read_b64_tr_b16 v[160:161], v210 offset:52352
	ds_read_b64_tr_b16 v[162:163], v210 offset:56704
	s_waitcnt lgkmcnt(8)
	v_mfma_f32_16x16x32_bf16 v[62:65], v[164:167], v[122:125], v[62:65]
	v_mfma_f32_16x16x32_bf16 v[58:61], v[164:167], v[134:137], v[58:61]
	ds_read_b64_tr_b16 v[164:165], v210 offset:61056
	ds_read_b64_tr_b16 v[166:167], v210 offset:65408
	s_waitcnt lgkmcnt(8)
	v_mfma_f32_16x16x32_bf16 v[62:65], v[148:151], v[114:117], v[62:65]
	v_mfma_f32_16x16x32_bf16 v[58:61], v[148:151], v[118:121], v[58:61]
	ds_read_b64_tr_b16 v[148:149], v210 offset:34976
	ds_read_b64_tr_b16 v[150:151], v210 offset:39328
	s_waitcnt lgkmcnt(8)
	v_mfma_f32_16x16x32_bf16 v[22:25], v[152:155], v[130:133], v[22:25]
	v_mfma_f32_16x16x32_bf16 v[18:21], v[152:155], v[142:145], v[18:21]
	ds_read_b64_tr_b16 v[152:153], v210 offset:43680
	ds_read_b64_tr_b16 v[154:155], v210 offset:48032
	s_waitcnt lgkmcnt(8)
	v_mfma_f32_16x16x32_bf16 v[22:25], v[156:159], v[126:129], v[22:25]
	v_mfma_f32_16x16x32_bf16 v[18:21], v[156:159], v[138:141], v[18:21]
	ds_read_b64_tr_b16 v[156:157], v210 offset:52384
	ds_read_b64_tr_b16 v[158:159], v210 offset:56736
	s_waitcnt lgkmcnt(8)
	v_mfma_f32_16x16x32_bf16 v[22:25], v[160:163], v[122:125], v[22:25]
	v_mfma_f32_16x16x32_bf16 v[18:21], v[160:163], v[134:137], v[18:21]
	ds_read_b64_tr_b16 v[160:161], v210 offset:61088
	ds_read_b64_tr_b16 v[162:163], v210 offset:65440
	s_waitcnt lgkmcnt(8)
	v_mfma_f32_16x16x32_bf16 v[22:25], v[164:167], v[114:117], v[22:25]
	v_mfma_f32_16x16x32_bf16 v[18:21], v[164:167], v[118:121], v[18:21]
	ds_read_b64_tr_b16 v[164:165], v210 offset:35008
	ds_read_b64_tr_b16 v[166:167], v210 offset:39360
	s_waitcnt lgkmcnt(8)
	v_mfma_f32_16x16x32_bf16 v[14:17], v[148:151], v[130:133], v[14:17]
	v_mfma_f32_16x16x32_bf16 v[10:13], v[148:151], v[142:145], v[10:13]
	ds_read_b64_tr_b16 v[148:149], v210 offset:43712
	ds_read_b64_tr_b16 v[150:151], v210 offset:48064
	s_waitcnt lgkmcnt(8)
	v_mfma_f32_16x16x32_bf16 v[14:17], v[152:155], v[126:129], v[14:17]
	v_mfma_f32_16x16x32_bf16 v[10:13], v[152:155], v[138:141], v[10:13]
	ds_read_b64_tr_b16 v[152:153], v210 offset:52416
	ds_read_b64_tr_b16 v[154:155], v210 offset:56768
	s_waitcnt lgkmcnt(8)
	v_mfma_f32_16x16x32_bf16 v[14:17], v[156:159], v[122:125], v[14:17]
	v_mfma_f32_16x16x32_bf16 v[10:13], v[156:159], v[134:137], v[10:13]
	ds_read_b64_tr_b16 v[156:157], v210 offset:61120
	ds_read_b64_tr_b16 v[158:159], v210 offset:65472
	s_waitcnt lgkmcnt(8)
	v_mfma_f32_16x16x32_bf16 v[14:17], v[160:163], v[114:117], v[14:17]
	v_mfma_f32_16x16x32_bf16 v[10:13], v[160:163], v[118:121], v[10:13]
	s_waitcnt lgkmcnt(6)
	v_mfma_f32_16x16x32_bf16 v[6:9], v[164:167], v[130:133], v[6:9]
	v_mfma_f32_16x16x32_bf16 v[2:5], v[164:167], v[142:145], v[2:5]
	s_waitcnt lgkmcnt(4)
	v_mfma_f32_16x16x32_bf16 v[6:9], v[148:151], v[126:129], v[6:9]
	v_mfma_f32_16x16x32_bf16 v[2:5], v[148:151], v[138:141], v[2:5]
	s_waitcnt lgkmcnt(2)
	v_mfma_f32_16x16x32_bf16 v[6:9], v[152:155], v[122:125], v[6:9]
	v_mfma_f32_16x16x32_bf16 v[2:5], v[152:155], v[134:137], v[2:5]
	s_waitcnt lgkmcnt(0)
	v_mfma_f32_16x16x32_bf16 v[6:9], v[156:159], v[114:117], v[6:9]
	v_mfma_f32_16x16x32_bf16 v[2:5], v[156:159], v[118:121], v[2:5]
	ds_read_b64_tr_b16 v[148:149], v210 offset:35040
	ds_read_b64_tr_b16 v[150:151], v210 offset:39392
	s_waitcnt lgkmcnt(0)
	v_mfma_f32_16x16x32_bf16 v[110:113], v[148:151], v[130:133], v[110:113]
	ds_read_b64_tr_b16 v[130:131], v210 offset:43744
	ds_read_b64_tr_b16 v[132:133], v210 offset:48096
	v_mfma_f32_16x16x32_bf16 v[106:109], v[148:151], v[142:145], v[106:109]
	s_waitcnt lgkmcnt(0)
	v_mfma_f32_16x16x32_bf16 v[110:113], v[130:133], v[126:129], v[110:113]
	v_mfma_f32_16x16x32_bf16 v[126:129], v[130:133], v[138:141], v[106:109]
	ds_read_b64_tr_b16 v[130:131], v210 offset:52448
	ds_read_b64_tr_b16 v[132:133], v210 offset:56800
	s_waitcnt lgkmcnt(0)
	v_mfma_f32_16x16x32_bf16 v[106:109], v[130:133], v[122:125], v[110:113]
	v_mfma_f32_16x16x32_bf16 v[122:125], v[130:133], v[134:137], v[126:129]
	s_nop 2
	ds_read_b64_tr_b16 v[126:127], v210 offset:61152
	ds_read_b64_tr_b16 v[128:129], v210 offset:65504
	s_waitcnt lgkmcnt(0)
	v_mfma_f32_16x16x32_bf16 v[110:113], v[126:129], v[114:117], v[106:109]
	v_mfma_f32_16x16x32_bf16 v[106:109], v[126:129], v[118:121], v[122:125]
	s_cbranch_scc0 .LBB0_239
	v_mov_b32_e32 v192, v214
	v_mov_b32_e32 v148, v213
	v_mov_b32_e32 v216, v146
	v_mov_b32_e32 v215, v147
	s_branch .LBB0_245
